# P5 row loop: the row's loads go out in two batches (second half after the first x loads have landed): fewer requests in flight
# speedup vs baseline: 1.0098x; 1.0098x over previous
; #define GAS __attribute__((address_space(1)))
; __device__ __forceinline__ float h_lo(unsigned w) { return (float)__builtin_bit_cast(_Float16, (unsigned short)(w & 0xffffu)); }
; __device__ __forceinline__ float h_hi(unsigned w) { return (float)__builtin_bit_cast(_Float16, (unsigned short)(w >> 16)); }
; template <bool SAMPLE, bool PRE = false> __device__ __forceinline__ void p5_row(Frame& F, int m, float* dst, const f32x4* xpre = nullptr) {
;     f32x4 v[16];
;     const GAS f32x4* x8 = (const GAS f32x4*)((SAMPLE ? F.in[2] + (size_t)(m - MP) * DM : F.in[0] + (size_t)m * DM)) + 2 * F.lane;
;     if (!SAMPLE) {
;         const GAS u32x4* yr = (const GAS u32x4*)(F.ws + WS_YH + (size_t)m * DM * 2) + F.lane;
;         u32x4 w[8];
; #pragma unroll
;         for (int j = 0; j < 8; ++j) { w[j] = yr[64 * j]; if constexpr (PRE) { v[2 * j] = xpre[2 * j]; v[2 * j + 1] = xpre[2 * j + 1]; } else { v[2 * j] = x8[128 * j]; v[2 * j + 1] = x8[128 * j + 1]; } }
; #pragma unroll
;         for (int j = 0; j < 8; ++j) { v[2 * j] += (f32x4){h_lo(w[j].x), h_hi(w[j].x), h_lo(w[j].y), h_hi(w[j].y)}; v[2 * j + 1] += (f32x4){h_lo(w[j].z), h_hi(w[j].z), h_lo(w[j].w), h_hi(w[j].w)}; }
.LBB0_842:
	v_lshl_add_u64 v[96:97], s[8:9], 0, v[130:131]
	global_load_dwordx4 v[12:15], v[94:95], off
	global_load_dwordx4 v[8:11], v[94:95], off offset:1024
	global_load_dwordx4 v[0:3], v[94:95], off offset:2048
	global_load_dwordx4 v[4:7], v[94:95], off offset:3072
	v_add_co_u32_e32 v136, vcc, 0x1000, v96
	v_lshl_add_u64 v[132:133], v[96:97], 0, s[4:5]
	s_nop 0
	v_addc_co_u32_e32 v137, vcc, 0, v97, vcc
	v_add_co_u32_e32 v156, vcc, 0x1000, v94
	v_lshl_add_u64 v[140:141], v[96:97], 0, s[12:13]
	s_nop 0
	v_addc_co_u32_e32 v157, vcc, 0, v95, vcc
	global_load_dwordx4 v[68:71], v[80:81], off offset:16
	global_load_dwordx4 v[76:79], v[80:81], off
	global_load_dwordx4 v[60:63], v[80:81], off offset:2064
	global_load_dwordx4 v[72:75], v[80:81], off offset:2048
	global_load_dwordx4 v[52:55], v[82:83], off offset:16
	global_load_dwordx4 v[64:67], v[82:83], off
	global_load_dwordx4 v[44:47], v[84:85], off offset:16
	global_load_dwordx4 v[56:59], v[84:85], off
	global_load_dwordx4 v[36:39], v[86:87], off offset:16
	global_load_dwordx4 v[48:51], v[86:87], off
	global_load_dwordx4 v[28:31], v[88:89], off offset:16
	global_load_dwordx4 v[40:43], v[88:89], off
	global_load_dwordx4 v[20:23], v[90:91], off offset:16
	global_load_dwordx4 v[32:35], v[90:91], off
	global_load_dwordx4 v[16:19], v[92:93], off offset:16
	global_load_dwordx4 v[24:27], v[92:93], off
	global_load_dwordx4 v[110:113], v[96:97], off offset:16
	global_load_dwordx4 v[114:117], v[96:97], off
	global_load_dwordx4 v[118:121], v[96:97], off offset:2064
	global_load_dwordx4 v[122:125], v[96:97], off offset:2048
	global_load_dwordx4 v[126:129], v[136:137], off
	s_nop 0
	global_load_dwordx4 v[132:135], v[132:133], off offset:16
	s_nop 0
	global_load_dwordx4 v[136:139], v[136:137], off offset:2048
	s_nop 0
	global_load_dwordx4 v[140:143], v[140:141], off offset:16
	s_waitcnt vmcnt(4)
	s_nop 0
	global_load_dwordx4 v[144:147], v[156:157], off
	global_load_dwordx4 v[148:151], v[156:157], off offset:1024
	global_load_dwordx4 v[152:155], v[156:157], off offset:2048
	v_add_co_u32_e32 v168, vcc, 0x2000, v96
	global_load_dwordx4 v[156:159], v[156:157], off offset:3072
	v_lshl_add_u64 v[164:165], v[96:97], 0, s[14:15]
	v_lshl_add_u64 v[172:173], v[96:97], 0, s[16:17]
	v_addc_co_u32_e32 v169, vcc, 0, v97, vcc
	global_load_dwordx4 v[160:163], v[168:169], off
	s_nop 0
	global_load_dwordx4 v[164:167], v[164:165], off offset:16
	s_nop 0
	global_load_dwordx4 v[168:171], v[168:169], off offset:2048
	s_nop 0
	global_load_dwordx4 v[172:175], v[172:173], off offset:16
	v_lshl_add_u64 v[180:181], v[96:97], 0, s[18:19]
	v_lshl_add_u64 v[188:189], v[96:97], 0, s[20:21]
	v_add_co_u32_e32 v96, vcc, 0x3000, v96
	v_lshl_add_u64 v[98:99], s[6:7], 0, v[130:131]
	s_nop 0
	v_addc_co_u32_e32 v97, vcc, 0, v97, vcc
	global_load_dwordx4 v[176:179], v[96:97], off
	s_nop 0
	global_load_dwordx4 v[180:183], v[180:181], off offset:16
	s_nop 0
	global_load_dwordx4 v[184:187], v[96:97], off offset:2048
	s_nop 0
	global_load_dwordx4 v[188:191], v[188:189], off offset:16
	v_add_co_u32_e64 v104, s[0:1], s23, v98
	v_mov_b32_e32 v109, 0
	s_nop 0
	v_addc_co_u32_e64 v105, s[0:1], 0, v99, s[0:1]
	v_add_co_u32_e64 v102, s[0:1], s24, v98
	v_mov_b32_e32 v208, 0
	s_nop 0
	v_addc_co_u32_e64 v103, s[0:1], 0, v99, s[0:1]
	v_add_co_u32_e64 v100, s[0:1], s25, v98
	s_add_i32 s22, s22, s28
	s_nop 0
	v_addc_co_u32_e64 v101, s[0:1], 0, v99, s[0:1]
	s_add_u32 s6, s6, s10
	s_addc_u32 s7, s7, s11
	s_add_u32 s8, s8, s10
	s_addc_u32 s9, s9, s11
	v_lshl_add_u64 v[94:95], v[94:95], 0, s[2:3]
	s_cmp_lt_i32 s22, s99
	s_waitcnt vmcnt(39)
	v_cvt_f32_f16_sdwa v97, v12 dst_sel:DWORD dst_unused:UNUSED_PAD src0_sel:WORD_1
	v_cvt_f32_f16_e32 v96, v12
	v_cvt_f32_f16_sdwa v193, v13 dst_sel:DWORD dst_unused:UNUSED_PAD src0_sel:WORD_1
	v_cvt_f32_f16_e32 v192, v13
	v_cvt_f32_f16_sdwa v13, v14 dst_sel:DWORD dst_unused:UNUSED_PAD src0_sel:WORD_1
	v_cvt_f32_f16_e32 v12, v14
	v_cvt_f32_f16_sdwa v195, v15 dst_sel:DWORD dst_unused:UNUSED_PAD src0_sel:WORD_1
	v_cvt_f32_f16_e32 v194, v15
	s_waitcnt vmcnt(38)
	v_cvt_f32_f16_sdwa v15, v8 dst_sel:DWORD dst_unused:UNUSED_PAD src0_sel:WORD_1
	v_cvt_f32_f16_e32 v14, v8
	v_cvt_f32_f16_sdwa v197, v9 dst_sel:DWORD dst_unused:UNUSED_PAD src0_sel:WORD_1
	v_cvt_f32_f16_e32 v196, v9
	v_cvt_f32_f16_sdwa v9, v10 dst_sel:DWORD dst_unused:UNUSED_PAD src0_sel:WORD_1
	v_cvt_f32_f16_e32 v8, v10
	v_cvt_f32_f16_sdwa v199, v11 dst_sel:DWORD dst_unused:UNUSED_PAD src0_sel:WORD_1
	v_cvt_f32_f16_e32 v198, v11
	s_waitcnt vmcnt(37)
	v_cvt_f32_f16_sdwa v11, v0 dst_sel:DWORD dst_unused:UNUSED_PAD src0_sel:WORD_1
	v_cvt_f32_f16_e32 v10, v0
	v_cvt_f32_f16_sdwa v201, v1 dst_sel:DWORD dst_unused:UNUSED_PAD src0_sel:WORD_1
	v_cvt_f32_f16_e32 v200, v1
	v_cvt_f32_f16_sdwa v1, v2 dst_sel:DWORD dst_unused:UNUSED_PAD src0_sel:WORD_1
	v_cvt_f32_f16_e32 v0, v2
	v_cvt_f32_f16_sdwa v203, v3 dst_sel:DWORD dst_unused:UNUSED_PAD src0_sel:WORD_1
	v_cvt_f32_f16_e32 v202, v3
	s_waitcnt vmcnt(36)
	v_cvt_f32_f16_sdwa v3, v4 dst_sel:DWORD dst_unused:UNUSED_PAD src0_sel:WORD_1
	v_cvt_f32_f16_e32 v2, v4
	v_cvt_f32_f16_sdwa v205, v5 dst_sel:DWORD dst_unused:UNUSED_PAD src0_sel:WORD_1
	v_cvt_f32_f16_e32 v204, v5
	v_cvt_f32_f16_sdwa v5, v6 dst_sel:DWORD dst_unused:UNUSED_PAD src0_sel:WORD_1
	v_cvt_f32_f16_e32 v4, v6
	v_cvt_f32_f16_sdwa v207, v7 dst_sel:DWORD dst_unused:UNUSED_PAD src0_sel:WORD_1
	v_cvt_f32_f16_e32 v206, v7
	s_waitcnt vmcnt(18)
	v_pk_add_f32 v[6:7], v[116:117], v[192:193]
	v_pk_add_f32 v[96:97], v[114:115], v[96:97]
	v_pk_add_f32 v[112:113], v[112:113], v[194:195]
	v_pk_add_f32 v[12:13], v[110:111], v[12:13]
	s_waitcnt vmcnt(16)
; #define GAS __attribute__((address_space(1)))
; __device__ __forceinline__ float h_lo(unsigned w) { return (float)__builtin_bit_cast(_Float16, (unsigned short)(w & 0xffffu)); }
; __device__ __forceinline__ float h_hi(unsigned w) { return (float)__builtin_bit_cast(_Float16, (unsigned short)(w >> 16)); }
; template <bool SAMPLE, bool PRE = false> __device__ __forceinline__ void p5_row(Frame& F, int m, float* dst, const f32x4* xpre = nullptr) {
;     ...
;         for (int j = 0; j < 8; ++j) { w[j] = yr[64 * j]; if constexpr (PRE) { v[2 * j] = xpre[2 * j]; v[2 * j + 1] = xpre[2 * j + 1]; } else { v[2 * j] = x8[128 * j]; v[2 * j + 1] = x8[128 * j + 1]; } }
; #pragma unroll
;         for (int j = 0; j < 8; ++j) { v[2 * j] += (f32x4){h_lo(w[j].x), h_hi(w[j].x), h_lo(w[j].y), h_hi(w[j].y)}; v[2 * j + 1] += (f32x4){h_lo(w[j].z), h_hi(w[j].z), h_lo(w[j].w), h_hi(w[j].w)}; }
;     } else {
; #pragma unroll
;         for (int j = 0; j < 8; ++j) { v[2 * j] = x8[128 * j]; v[2 * j + 1] = x8[128 * j + 1]; }
; #pragma unroll 2
;         for (int p = 0; p < 8; ++p) { const GAS u32x4* pr = (const GAS u32x4*)(F.ws + WS_SLAB + ((size_t)p * MS + (m - MP)) * DM * 2) + F.lane;
;             u32x4 w[8];
; #pragma unroll
;             for (int j = 0; j < 8; ++j) w[j] = pr[64 * j];
; #pragma unroll
;             for (int j = 0; j < 8; ++j) { v[2 * j] += (f32x4){h_lo(w[j].x), h_hi(w[j].x), h_lo(w[j].y), h_hi(w[j].y)}; v[2 * j + 1] += (f32x4){h_lo(w[j].z), h_hi(w[j].z), h_lo(w[j].w), h_hi(w[j].w)}; } }
;     }
;     float s = 0.f;
; #pragma unroll
;     for (int j = 0; j < 16; ++j) s += (v[j].x * v[j].x + v[j].y * v[j].y) + (v[j].z * v[j].z + v[j].w * v[j].w);
	v_pk_add_f32 v[110:111], v[124:125], v[196:197]
	v_pk_add_f32 v[14:15], v[122:123], v[14:15]
	v_pk_add_f32 v[114:115], v[120:121], v[198:199]
	v_pk_add_f32 v[8:9], v[118:119], v[8:9]
	s_waitcnt vmcnt(15)
	v_pk_add_f32 v[116:117], v[128:129], v[200:201]
	v_pk_add_f32 v[10:11], v[126:127], v[10:11]
	s_waitcnt vmcnt(14)
	v_pk_add_f32 v[118:119], v[134:135], v[202:203]
	v_pk_add_f32 v[0:1], v[132:133], v[0:1]
	s_waitcnt vmcnt(13)
	v_pk_add_f32 v[120:121], v[138:139], v[204:205]
	v_pk_add_f32 v[2:3], v[136:137], v[2:3]
	s_waitcnt vmcnt(12)
	v_pk_add_f32 v[122:123], v[142:143], v[206:207]
	v_pk_add_f32 v[4:5], v[140:141], v[4:5]
	s_waitcnt vmcnt(11)
	v_cvt_f32_f16_e32 v124, v144
	v_cvt_f32_f16_sdwa v125, v144 dst_sel:DWORD dst_unused:UNUSED_PAD src0_sel:WORD_1
	v_cvt_f32_f16_e32 v126, v145
	v_cvt_f32_f16_sdwa v127, v145 dst_sel:DWORD dst_unused:UNUSED_PAD src0_sel:WORD_1
	v_cvt_f32_f16_e32 v128, v146
	v_cvt_f32_f16_sdwa v129, v146 dst_sel:DWORD dst_unused:UNUSED_PAD src0_sel:WORD_1
	v_cvt_f32_f16_e32 v132, v147
	v_cvt_f32_f16_sdwa v133, v147 dst_sel:DWORD dst_unused:UNUSED_PAD src0_sel:WORD_1
	s_waitcnt vmcnt(10)
	v_cvt_f32_f16_e32 v134, v148
	v_cvt_f32_f16_sdwa v135, v148 dst_sel:DWORD dst_unused:UNUSED_PAD src0_sel:WORD_1
	v_cvt_f32_f16_e32 v136, v149
	v_cvt_f32_f16_sdwa v137, v149 dst_sel:DWORD dst_unused:UNUSED_PAD src0_sel:WORD_1
	v_cvt_f32_f16_e32 v138, v150
	v_cvt_f32_f16_sdwa v139, v150 dst_sel:DWORD dst_unused:UNUSED_PAD src0_sel:WORD_1
	v_cvt_f32_f16_e32 v140, v151
	v_cvt_f32_f16_sdwa v141, v151 dst_sel:DWORD dst_unused:UNUSED_PAD src0_sel:WORD_1
	s_waitcnt vmcnt(9)
	v_cvt_f32_f16_e32 v142, v152
	v_cvt_f32_f16_sdwa v143, v152 dst_sel:DWORD dst_unused:UNUSED_PAD src0_sel:WORD_1
	v_cvt_f32_f16_e32 v144, v153
	v_cvt_f32_f16_sdwa v145, v153 dst_sel:DWORD dst_unused:UNUSED_PAD src0_sel:WORD_1
	v_cvt_f32_f16_e32 v146, v154
	v_cvt_f32_f16_sdwa v147, v154 dst_sel:DWORD dst_unused:UNUSED_PAD src0_sel:WORD_1
	v_cvt_f32_f16_e32 v148, v155
	v_cvt_f32_f16_sdwa v149, v155 dst_sel:DWORD dst_unused:UNUSED_PAD src0_sel:WORD_1
	s_waitcnt vmcnt(8)
	v_cvt_f32_f16_e32 v150, v156
	v_cvt_f32_f16_sdwa v151, v156 dst_sel:DWORD dst_unused:UNUSED_PAD src0_sel:WORD_1
	v_cvt_f32_f16_e32 v152, v157
	v_cvt_f32_f16_sdwa v153, v157 dst_sel:DWORD dst_unused:UNUSED_PAD src0_sel:WORD_1
	v_cvt_f32_f16_e32 v154, v158
	v_cvt_f32_f16_sdwa v155, v158 dst_sel:DWORD dst_unused:UNUSED_PAD src0_sel:WORD_1
	v_cvt_f32_f16_e32 v156, v159
	v_cvt_f32_f16_sdwa v157, v159 dst_sel:DWORD dst_unused:UNUSED_PAD src0_sel:WORD_1
	v_mul_f32_e32 v158, v97, v97
	v_mul_f32_e32 v159, v7, v7
	v_mul_f32_e32 v192, v13, v13
	v_mul_f32_e32 v193, v113, v113
	v_mul_f32_e32 v194, v15, v15
	v_mul_f32_e32 v195, v111, v111
	v_fmac_f32_e32 v158, v96, v96
	v_fmac_f32_e32 v159, v6, v6
	v_fmac_f32_e32 v192, v12, v12
	v_fmac_f32_e32 v193, v112, v112
	v_mul_f32_e32 v196, v9, v9
	v_mul_f32_e32 v197, v115, v115
	v_fmac_f32_e32 v194, v14, v14
	v_fmac_f32_e32 v195, v110, v110
	v_add_f32_e32 v158, v158, v159
	v_add_f32_e32 v159, v192, v193
	v_mul_f32_e32 v198, v11, v11
	v_mul_f32_e32 v199, v117, v117
	v_fmac_f32_e32 v196, v8, v8
	v_fmac_f32_e32 v197, v114, v114
	v_add_f32_e32 v192, v194, v195
	v_add_f32_e32 v158, v158, v159
	v_mul_f32_e32 v200, v1, v1
	v_mul_f32_e32 v201, v119, v119
	v_fmac_f32_e32 v198, v10, v10
	v_fmac_f32_e32 v199, v116, v116
	v_add_f32_e32 v193, v196, v197
	v_add_f32_e32 v158, v158, v192
	v_mul_f32_e32 v202, v3, v3
	v_mul_f32_e32 v203, v121, v121
	v_fmac_f32_e32 v200, v0, v0
	v_fmac_f32_e32 v201, v118, v118
	v_add_f32_e32 v194, v198, v199
	v_add_f32_e32 v158, v193, v158
	v_mul_f32_e32 v204, v5, v5
	v_mul_f32_e32 v205, v123, v123
	v_fmac_f32_e32 v202, v2, v2
	v_fmac_f32_e32 v203, v120, v120
	v_add_f32_e32 v195, v200, v201
	s_waitcnt vmcnt(7)
	v_pk_add_f32 v[126:127], v[162:163], v[126:127]
	v_pk_add_f32 v[124:125], v[160:161], v[124:125]
	v_add_f32_e32 v158, v158, v194
	v_fmac_f32_e32 v204, v4, v4
	v_fmac_f32_e32 v205, v122, v122
	v_add_f32_e32 v196, v202, v203
	s_waitcnt vmcnt(6)
	v_pk_add_f32 v[132:133], v[166:167], v[132:133]
	v_pk_add_f32 v[128:129], v[164:165], v[128:129]
	v_mul_f32_e32 v159, v125, v125
	v_mul_f32_e32 v160, v127, v127
	v_add_f32_e32 v158, v195, v158
	v_add_f32_e32 v197, v204, v205
	s_waitcnt vmcnt(5)
	v_pk_add_f32 v[136:137], v[170:171], v[136:137]
	v_pk_add_f32 v[134:135], v[168:169], v[134:135]
	v_mul_f32_e32 v161, v129, v129
	v_mul_f32_e32 v162, v133, v133
	v_fmac_f32_e32 v159, v124, v124
	v_fmac_f32_e32 v160, v126, v126
	v_add_f32_e32 v158, v158, v196
	s_waitcnt vmcnt(4)
	v_pk_add_f32 v[140:141], v[174:175], v[140:141]
	v_pk_add_f32 v[138:139], v[172:173], v[138:139]
	v_mul_f32_e32 v163, v135, v135
	v_mul_f32_e32 v164, v137, v137
	v_fmac_f32_e32 v161, v128, v128
	v_fmac_f32_e32 v162, v132, v132
	v_add_f32_e32 v159, v159, v160
	v_add_f32_e32 v158, v197, v158
	s_waitcnt vmcnt(3)
	v_pk_add_f32 v[144:145], v[178:179], v[144:145]
	v_pk_add_f32 v[142:143], v[176:177], v[142:143]
	v_mul_f32_e32 v165, v139, v139
	v_mul_f32_e32 v166, v141, v141
	v_fmac_f32_e32 v163, v134, v134
	v_fmac_f32_e32 v164, v136, v136
	v_add_f32_e32 v160, v161, v162
	v_add_f32_e32 v158, v158, v159
	s_waitcnt vmcnt(2)
	v_pk_add_f32 v[148:149], v[182:183], v[148:149]
	v_pk_add_f32 v[146:147], v[180:181], v[146:147]
	v_mul_f32_e32 v167, v143, v143
	v_mul_f32_e32 v168, v145, v145
	v_fmac_f32_e32 v165, v138, v138
	v_fmac_f32_e32 v166, v140, v140
	v_add_f32_e32 v161, v163, v164
	v_add_f32_e32 v158, v160, v158
	s_waitcnt vmcnt(1)
	v_pk_add_f32 v[152:153], v[186:187], v[152:153]
	v_pk_add_f32 v[150:151], v[184:185], v[150:151]
	v_mul_f32_e32 v169, v147, v147
	v_mul_f32_e32 v170, v149, v149
	v_fmac_f32_e32 v167, v142, v142
	v_fmac_f32_e32 v168, v144, v144
	v_add_f32_e32 v162, v165, v166
	v_add_f32_e32 v158, v158, v161
	s_waitcnt vmcnt(0)
; #define GAS __attribute__((address_space(1)))
; template <bool SAMPLE, bool PRE = false> __device__ __forceinline__ void p5_row(Frame& F, int m, float* dst, const f32x4* xpre = nullptr) {
;     ...
;     float s = 0.f;
; #pragma unroll
;     for (int j = 0; j < 16; ++j) s += (v[j].x * v[j].x + v[j].y * v[j].y) + (v[j].z * v[j].z + v[j].w * v[j].w);
;     const float rstd = 1.0f / sqrtf(wave_sum(s) * (1.0f / DM) + EPS);
;     const GAS f32x4* g8 = (const GAS f32x4*)F.in[20] + 2 * F.lane; GAS f32x4* y8 = (GAS f32x4*)(dst + (size_t)m * DM) + 2 * F.lane;
;     f32x4 gv[16];
; #pragma unroll
;     for (int j = 0; j < 8; ++j) { gv[2 * j] = g8[128 * j]; gv[2 * j + 1] = g8[128 * j + 1]; }
; #pragma unroll
;     for (int j = 0; j < 8; ++j) { y8[128 * j] = v[2 * j] * rstd * gv[2 * j]; y8[128 * j + 1] = v[2 * j + 1] * rstd * gv[2 * j + 1]; }
	v_pk_add_f32 v[156:157], v[190:191], v[156:157]
	v_pk_add_f32 v[154:155], v[188:189], v[154:155]
	v_mul_f32_e32 v171, v151, v151
	v_mul_f32_e32 v172, v153, v153
	v_fmac_f32_e32 v169, v146, v146
	v_fmac_f32_e32 v170, v148, v148
	v_add_f32_e32 v163, v167, v168
	v_add_f32_e32 v158, v162, v158
	v_mul_f32_e32 v173, v155, v155
	v_mul_f32_e32 v174, v157, v157
	v_fmac_f32_e32 v171, v150, v150
	v_fmac_f32_e32 v172, v152, v152
	v_add_f32_e32 v164, v169, v170
	v_add_f32_e32 v158, v158, v163
	v_fmac_f32_e32 v173, v154, v154
	v_fmac_f32_e32 v174, v156, v156
	v_add_f32_e32 v165, v171, v172
	v_add_f32_e32 v158, v164, v158
	v_add_f32_e32 v166, v173, v174
	v_add_f32_e32 v158, v158, v165
	v_add_f32_e32 v158, v166, v158
	s_nop 1
	v_add_f32_dpp v158, v158, v158 quad_perm:[1,0,3,2] row_mask:0xf bank_mask:0xf bound_ctrl:1
	s_nop 1
	v_add_f32_dpp v158, v158, v158 quad_perm:[2,3,0,1] row_mask:0xf bank_mask:0xf bound_ctrl:1
	s_nop 1
	v_add_f32_dpp v158, v158, v158 row_half_mirror row_mask:0xf bank_mask:0xf bound_ctrl:1
	s_nop 1
	v_add_f32_dpp v158, v158, v158 row_mirror row_mask:0xf bank_mask:0xf bound_ctrl:1
	s_nop 1
	v_mov_b32_dpp v109, v158 row_bcast:15 row_mask:0xa bank_mask:0xf
	v_add_f32_e32 v109, v158, v109
	s_nop 1
	v_mov_b32_dpp v208, v109 row_bcast:31 row_mask:0xc bank_mask:0xf
	v_add_f32_e32 v109, v109, v208
	s_nop 0
	v_readlane_b32 s0, v109, 63
	s_nop 1
	v_fma_f32 v109, s0, v107, v106
	v_mul_f32_e32 v158, 0x4f800000, v109
	v_cmp_gt_f32_e32 vcc, s26, v109
	s_nop 1
	v_cndmask_b32_e32 v109, v109, v158, vcc
	v_sqrt_f32_e32 v158, v109
	s_nop 0
	v_add_u32_e32 v159, -1, v158
	v_add_u32_e32 v160, 1, v158
	v_fma_f32 v161, -v159, v158, v109
	v_fma_f32 v162, -v160, v158, v109
	v_cmp_ge_f32_e64 s[0:1], 0, v161
	s_nop 1
	v_cndmask_b32_e64 v158, v158, v159, s[0:1]
	v_cmp_lt_f32_e64 s[0:1], 0, v162
	s_nop 1
	v_cndmask_b32_e64 v158, v158, v160, s[0:1]
	v_mul_f32_e32 v159, 0x37800000, v158
	v_cndmask_b32_e32 v158, v158, v159, vcc
	v_cmp_class_f32_e32 vcc, v109, v108
	s_nop 1
	v_cndmask_b32_e32 v109, v158, v109, vcc
	v_div_scale_f32 v158, s[0:1], v109, v109, 1.0
	v_rcp_f32_e32 v160, v158
	v_div_scale_f32 v159, vcc, 1.0, v109, 1.0
	v_fma_f32 v161, -v158, v160, 1.0
	v_fmac_f32_e32 v160, v161, v160
	v_mul_f32_e32 v161, v159, v160
	v_fma_f32 v162, -v158, v161, v159
	v_fmac_f32_e32 v161, v162, v160
	v_fma_f32 v158, -v158, v161, v159
	v_div_fmas_f32 v158, v158, v160, v161
	v_div_fixup_f32 v158, v158, v109, 1.0
	v_pk_mul_f32 v[96:97], v[96:97], v[158:159] op_sel_hi:[1,0]
	v_pk_mul_f32 v[6:7], v[6:7], v[158:159] op_sel_hi:[1,0]
	v_pk_mul_f32 v[12:13], v[12:13], v[158:159] op_sel_hi:[1,0]
	v_pk_mul_f32 v[112:113], v[112:113], v[158:159] op_sel_hi:[1,0]
	v_pk_mul_f32 v[14:15], v[14:15], v[158:159] op_sel_hi:[1,0]
	v_pk_mul_f32 v[110:111], v[110:111], v[158:159] op_sel_hi:[1,0]
	v_pk_mul_f32 v[160:161], v[8:9], v[158:159] op_sel_hi:[1,0]
	v_pk_mul_f32 v[114:115], v[114:115], v[158:159] op_sel_hi:[1,0]
	v_pk_mul_f32 v[162:163], v[10:11], v[158:159] op_sel_hi:[1,0]
	v_pk_mul_f32 v[116:117], v[116:117], v[158:159] op_sel_hi:[1,0]
	v_pk_mul_f32 v[164:165], v[0:1], v[158:159] op_sel_hi:[1,0]
	v_pk_mul_f32 v[118:119], v[118:119], v[158:159] op_sel_hi:[1,0]
	v_pk_mul_f32 v[166:167], v[2:3], v[158:159] op_sel_hi:[1,0]
	v_pk_mul_f32 v[120:121], v[120:121], v[158:159] op_sel_hi:[1,0]
	v_pk_mul_f32 v[168:169], v[4:5], v[158:159] op_sel_hi:[1,0]
	v_pk_mul_f32 v[122:123], v[122:123], v[158:159] op_sel_hi:[1,0]
	v_pk_mul_f32 v[124:125], v[124:125], v[158:159] op_sel_hi:[1,0]
	v_pk_mul_f32 v[126:127], v[126:127], v[158:159] op_sel_hi:[1,0]
	v_pk_mul_f32 v[128:129], v[128:129], v[158:159] op_sel_hi:[1,0]
	v_pk_mul_f32 v[132:133], v[132:133], v[158:159] op_sel_hi:[1,0]
	v_pk_mul_f32 v[134:135], v[134:135], v[158:159] op_sel_hi:[1,0]
	v_pk_mul_f32 v[136:137], v[136:137], v[158:159] op_sel_hi:[1,0]
	v_pk_mul_f32 v[138:139], v[138:139], v[158:159] op_sel_hi:[1,0]
	v_pk_mul_f32 v[140:141], v[140:141], v[158:159] op_sel_hi:[1,0]
	v_pk_mul_f32 v[142:143], v[142:143], v[158:159] op_sel_hi:[1,0]
	v_pk_mul_f32 v[144:145], v[144:145], v[158:159] op_sel_hi:[1,0]
	v_pk_mul_f32 v[146:147], v[146:147], v[158:159] op_sel_hi:[1,0]
	v_pk_mul_f32 v[148:149], v[148:149], v[158:159] op_sel_hi:[1,0]
	v_pk_mul_f32 v[150:151], v[150:151], v[158:159] op_sel_hi:[1,0]
	v_pk_mul_f32 v[152:153], v[152:153], v[158:159] op_sel_hi:[1,0]
	v_pk_mul_f32 v[154:155], v[154:155], v[158:159] op_sel_hi:[1,0]
	v_pk_mul_f32 v[156:157], v[156:157], v[158:159] op_sel_hi:[1,0]
	v_pk_mul_f32 v[2:3], v[78:79], v[6:7]
	v_pk_mul_f32 v[0:1], v[76:77], v[96:97]
	v_pk_mul_f32 v[6:7], v[70:71], v[112:113]
	v_pk_mul_f32 v[4:5], v[68:69], v[12:13]
	v_pk_mul_f32 v[10:11], v[74:75], v[110:111]
	v_pk_mul_f32 v[8:9], v[72:73], v[14:15]
	v_pk_mul_f32 v[14:15], v[62:63], v[114:115]
	v_pk_mul_f32 v[12:13], v[60:61], v[160:161]
	v_pk_mul_f32 v[62:63], v[66:67], v[116:117]
	v_pk_mul_f32 v[60:61], v[64:65], v[162:163]
	v_pk_mul_f32 v[54:55], v[54:55], v[118:119]
	v_pk_mul_f32 v[52:53], v[52:53], v[164:165]
	v_pk_mul_f32 v[58:59], v[120:121], v[58:59]
	v_pk_mul_f32 v[56:57], v[166:167], v[56:57]
	v_pk_mul_f32 v[46:47], v[122:123], v[46:47]
	v_pk_mul_f32 v[44:45], v[168:169], v[44:45]
	v_pk_mul_f32 v[50:51], v[126:127], v[50:51]
	v_pk_mul_f32 v[48:49], v[124:125], v[48:49]
	v_pk_mul_f32 v[38:39], v[132:133], v[38:39]
	v_pk_mul_f32 v[36:37], v[128:129], v[36:37]
	v_pk_mul_f32 v[42:43], v[136:137], v[42:43]
	v_pk_mul_f32 v[40:41], v[134:135], v[40:41]
	v_pk_mul_f32 v[30:31], v[140:141], v[30:31]
	v_pk_mul_f32 v[28:29], v[138:139], v[28:29]
	v_pk_mul_f32 v[34:35], v[144:145], v[34:35]
	v_pk_mul_f32 v[32:33], v[142:143], v[32:33]
	v_pk_mul_f32 v[22:23], v[148:149], v[22:23]
	v_pk_mul_f32 v[20:21], v[146:147], v[20:21]
	v_pk_mul_f32 v[26:27], v[152:153], v[26:27]
	v_pk_mul_f32 v[24:25], v[150:151], v[24:25]
	v_pk_mul_f32 v[18:19], v[156:157], v[18:19]
	v_pk_mul_f32 v[16:17], v[154:155], v[16:17]
	global_store_dwordx4 v[98:99], v[0:3], off
	global_store_dwordx4 v[98:99], v[4:7], off offset:16
	global_store_dwordx4 v[98:99], v[8:11], off offset:2048
	global_store_dwordx4 v[98:99], v[12:15], off offset:2064
	global_store_dwordx4 v[102:103], v[60:63], off offset:-4096
	global_store_dwordx4 v[104:105], v[52:55], off offset:16
	global_store_dwordx4 v[104:105], v[56:59], off offset:2048
	global_store_dwordx4 v[104:105], v[44:47], off offset:2064
	global_store_dwordx4 v[102:103], v[48:51], off
	global_store_dwordx4 v[102:103], v[36:39], off offset:16
	global_store_dwordx4 v[102:103], v[40:43], off offset:2048
	global_store_dwordx4 v[102:103], v[28:31], off offset:2064
	global_store_dwordx4 v[100:101], v[32:35], off
	global_store_dwordx4 v[100:101], v[20:23], off offset:16
	global_store_dwordx4 v[100:101], v[24:27], off offset:2048
	global_store_dwordx4 v[100:101], v[16:19], off offset:2064
	s_cbranch_scc1 .LBB0_842
